# p0a folded weight tiles: the two 64x64x64 f32 products per item moved from VALU+LDS dot loops to v_mfma_f32_16x16x4_f32 (f32 operands, f32 accumulate)
# speedup vs baseline: 1.0205x; 1.0205x over previous
.LBB0_59:
	s_lshl_b32 s8, s4, 6
	s_cmp_eq_u32 s5, 1
	s_cselect_b64 s[4:5], -1, 0
	s_and_b64 s[14:15], s[4:5], exec
	s_cselect_b32 s14, 0, 0x100
	s_add_i32 s29, s14, 0
	s_lshl_b32 s14, s26, 8
	s_or_b32 s30, s8, s14
	v_or_b32_e32 v12, s30, v4
	v_readlane_b32 s80, v254, 2
	v_ashrrev_i32_e32 v13, 31, v12
	v_readlane_b32 s84, v254, 6
	v_readlane_b32 s85, v254, 7
	s_mov_b32 s28, 0
	v_cndmask_b32_e64 v42, v40, v41, s[4:5]
	v_lshl_add_u64 v[12:13], v[12:13], 2, s[84:85]
	s_waitcnt lgkmcnt(0)
	s_barrier
	v_readlane_b32 s81, v254, 3
	v_readlane_b32 s82, v254, 4
	v_readlane_b32 s83, v254, 5
	v_readlane_b32 s86, v254, 8
	v_readlane_b32 s87, v254, 9
	v_readlane_b32 s88, v254, 10
	v_readlane_b32 s89, v254, 11
	v_readlane_b32 s90, v254, 12
	v_readlane_b32 s91, v254, 13
	v_readlane_b32 s92, v254, 14
	v_readlane_b32 s93, v254, 15
	v_readlane_b32 s94, v254, 16
	v_readlane_b32 s95, v254, 17
	s_and_b64 vcc, exec, s[12:13]
	s_cbranch_vccz .LBB0_61
	v_and_b32_e32 v43, 15, v2
	v_lshrrev_b32_e32 v44, 4, v2
	s_lshr_b32 s14, s16, 1
	s_and_b32 s15, s16, 1
	v_lshl_add_u32 v45, s14, 4, v43
	s_lshl_b32 s15, s15, 5
	v_mul_u32_u24_e32 v46, v45, v44
	v_lshlrev_b32_e32 v47, 2, v45
	v_lshl_add_u32 v48, v44, 6, v43
	v_add_lshl_u32 v48, v48, s15, 2
	v_and_b32_e32 v49, 63, v46
	v_lshl_add_u32 v49, v49, 2, s29
	v_add_u32_e32 v46, v46, v47
	ds_read_b32 v54, v49 offset:33024
	ds_read_b32 v62, v48 offset:46080
	ds_read_b32 v70, v48 offset:46144
	v_and_b32_e32 v49, 63, v46
	v_lshl_add_u32 v49, v49, 2, s29
	v_add_u32_e32 v46, v46, v47
	ds_read_b32 v55, v49 offset:33024
	ds_read_b32 v63, v48 offset:47104
	ds_read_b32 v71, v48 offset:47168
	v_and_b32_e32 v49, 63, v46
	v_lshl_add_u32 v49, v49, 2, s29
	v_add_u32_e32 v46, v46, v47
	ds_read_b32 v56, v49 offset:33024
	ds_read_b32 v64, v48 offset:48128
	ds_read_b32 v72, v48 offset:48192
	v_and_b32_e32 v49, 63, v46
	v_lshl_add_u32 v49, v49, 2, s29
	v_add_u32_e32 v46, v46, v47
	ds_read_b32 v57, v49 offset:33024
	ds_read_b32 v65, v48 offset:49152
	ds_read_b32 v73, v48 offset:49216
	v_and_b32_e32 v49, 63, v46
	v_lshl_add_u32 v49, v49, 2, s29
	v_add_u32_e32 v46, v46, v47
	ds_read_b32 v58, v49 offset:33024
	ds_read_b32 v66, v48 offset:50176
	ds_read_b32 v74, v48 offset:50240
	v_and_b32_e32 v49, 63, v46
	v_lshl_add_u32 v49, v49, 2, s29
	v_add_u32_e32 v46, v46, v47
	ds_read_b32 v59, v49 offset:33024
	ds_read_b32 v67, v48 offset:51200
	ds_read_b32 v75, v48 offset:51264
	v_and_b32_e32 v49, 63, v46
	v_lshl_add_u32 v49, v49, 2, s29
	v_add_u32_e32 v46, v46, v47
	ds_read_b32 v60, v49 offset:33024
	ds_read_b32 v68, v48 offset:52224
	ds_read_b32 v76, v48 offset:52288
	v_and_b32_e32 v49, 63, v46
	v_lshl_add_u32 v49, v49, 2, s29
	v_add_u32_e32 v46, v46, v47
	ds_read_b32 v61, v49 offset:33024
	ds_read_b32 v69, v48 offset:53248
	ds_read_b32 v77, v48 offset:53312
	s_waitcnt lgkmcnt(0)
	v_mfma_f32_16x16x4_f32 v[78:81], v54, v62, 0
	v_mfma_f32_16x16x4_f32 v[82:85], v54, v70, 0
	v_mfma_f32_16x16x4_f32 v[78:81], v55, v63, v[78:81]
	v_mfma_f32_16x16x4_f32 v[82:85], v55, v71, v[82:85]
	v_mfma_f32_16x16x4_f32 v[78:81], v56, v64, v[78:81]
	v_mfma_f32_16x16x4_f32 v[82:85], v56, v72, v[82:85]
	v_mfma_f32_16x16x4_f32 v[78:81], v57, v65, v[78:81]
	v_mfma_f32_16x16x4_f32 v[82:85], v57, v73, v[82:85]
	v_mfma_f32_16x16x4_f32 v[78:81], v58, v66, v[78:81]
	v_mfma_f32_16x16x4_f32 v[82:85], v58, v74, v[82:85]
	v_mfma_f32_16x16x4_f32 v[78:81], v59, v67, v[78:81]
	v_mfma_f32_16x16x4_f32 v[82:85], v59, v75, v[82:85]
	v_mfma_f32_16x16x4_f32 v[78:81], v60, v68, v[78:81]
	v_mfma_f32_16x16x4_f32 v[82:85], v60, v76, v[82:85]
	v_mfma_f32_16x16x4_f32 v[78:81], v61, v69, v[78:81]
	v_mfma_f32_16x16x4_f32 v[82:85], v61, v77, v[82:85]
	v_and_b32_e32 v49, 63, v46
	v_lshl_add_u32 v49, v49, 2, s29
	v_add_u32_e32 v46, v46, v47
	ds_read_b32 v54, v49 offset:33024
	ds_read_b32 v62, v48 offset:54272
	ds_read_b32 v70, v48 offset:54336
	v_and_b32_e32 v49, 63, v46
	v_lshl_add_u32 v49, v49, 2, s29
	v_add_u32_e32 v46, v46, v47
	ds_read_b32 v55, v49 offset:33024
	ds_read_b32 v63, v48 offset:55296
	ds_read_b32 v71, v48 offset:55360
	v_and_b32_e32 v49, 63, v46
	v_lshl_add_u32 v49, v49, 2, s29
	v_add_u32_e32 v46, v46, v47
	ds_read_b32 v56, v49 offset:33024
	ds_read_b32 v64, v48 offset:56320
	ds_read_b32 v72, v48 offset:56384
	v_and_b32_e32 v49, 63, v46
	v_lshl_add_u32 v49, v49, 2, s29
	v_add_u32_e32 v46, v46, v47
	ds_read_b32 v57, v49 offset:33024
	ds_read_b32 v65, v48 offset:57344
	ds_read_b32 v73, v48 offset:57408
	v_and_b32_e32 v49, 63, v46
	v_lshl_add_u32 v49, v49, 2, s29
	v_add_u32_e32 v46, v46, v47
	ds_read_b32 v58, v49 offset:33024
	ds_read_b32 v66, v48 offset:58368
	ds_read_b32 v74, v48 offset:58432
	v_and_b32_e32 v49, 63, v46
	v_lshl_add_u32 v49, v49, 2, s29
	v_add_u32_e32 v46, v46, v47
	ds_read_b32 v59, v49 offset:33024
	ds_read_b32 v67, v48 offset:59392
	ds_read_b32 v75, v48 offset:59456
	v_and_b32_e32 v49, 63, v46
	v_lshl_add_u32 v49, v49, 2, s29
	v_add_u32_e32 v46, v46, v47
	ds_read_b32 v60, v49 offset:33024
	ds_read_b32 v68, v48 offset:60416
	ds_read_b32 v76, v48 offset:60480
	v_and_b32_e32 v49, 63, v46
	v_lshl_add_u32 v49, v49, 2, s29
	v_add_u32_e32 v46, v46, v47
	ds_read_b32 v61, v49 offset:33024
	ds_read_b32 v69, v48 offset:61440
	ds_read_b32 v77, v48 offset:61504
	s_waitcnt lgkmcnt(0)
	v_mfma_f32_16x16x4_f32 v[78:81], v54, v62, v[78:81]
	v_mfma_f32_16x16x4_f32 v[82:85], v54, v70, v[82:85]
	v_mfma_f32_16x16x4_f32 v[78:81], v55, v63, v[78:81]
	v_mfma_f32_16x16x4_f32 v[82:85], v55, v71, v[82:85]
	v_mfma_f32_16x16x4_f32 v[78:81], v56, v64, v[78:81]
	v_mfma_f32_16x16x4_f32 v[82:85], v56, v72, v[82:85]
	v_mfma_f32_16x16x4_f32 v[78:81], v57, v65, v[78:81]
	v_mfma_f32_16x16x4_f32 v[82:85], v57, v73, v[82:85]
	v_mfma_f32_16x16x4_f32 v[78:81], v58, v66, v[78:81]
	v_mfma_f32_16x16x4_f32 v[82:85], v58, v74, v[82:85]
	v_mfma_f32_16x16x4_f32 v[78:81], v59, v67, v[78:81]
	v_mfma_f32_16x16x4_f32 v[82:85], v59, v75, v[82:85]
	v_mfma_f32_16x16x4_f32 v[78:81], v60, v68, v[78:81]
	v_mfma_f32_16x16x4_f32 v[82:85], v60, v76, v[82:85]
	v_mfma_f32_16x16x4_f32 v[78:81], v61, v69, v[78:81]
	v_mfma_f32_16x16x4_f32 v[82:85], v61, v77, v[82:85]
	v_lshlrev_b32_e32 v49, 2, v44
	v_lshl_add_u32 v49, s14, 4, v49
	v_lshl_add_u32 v49, v49, 6, v43
	v_add_lshl_u32 v49, v49, s15, 2
	s_nop 7
	s_nop 3
	v_mul_f32_e32 v78, v42, v78
	v_mul_f32_e32 v79, v42, v79
	v_mul_f32_e32 v80, v42, v80
	v_mul_f32_e32 v81, v42, v81
	v_mul_f32_e32 v82, v42, v82
	v_mul_f32_e32 v83, v42, v83
	v_mul_f32_e32 v84, v42, v84
	v_mul_f32_e32 v85, v42, v85
	ds_write_b32 v49, v78
	ds_write_b32 v49, v79 offset:256
	ds_write_b32 v49, v80 offset:512
	ds_write_b32 v49, v81 offset:768
	ds_write_b32 v49, v82 offset:64
	ds_write_b32 v49, v83 offset:320
	ds_write_b32 v49, v84 offset:576
	ds_write_b32 v49, v85 offset:832
	s_branch .LBB0_67

.LBB0_67:
	s_waitcnt lgkmcnt(0)
	s_barrier
	v_and_b32_e32 v42, 15, v2
	v_lshrrev_b32_e32 v43, 4, v2
	s_lshr_b32 s12, s16, 1
	s_and_b32 s13, s16, 1
	v_lshl_add_u32 v44, s12, 4, v42
	s_lshl_b32 s13, s13, 5
	v_mul_u32_u24_e32 v44, 0x41, v44
	v_lshl_add_u32 v45, v43, 6, v42
	v_add_lshl_u32 v44, v44, v43, 2
	v_add_lshl_u32 v45, v45, s13, 2
	ds_read_b32 v46, v44 offset:16384
	ds_read_b32 v54, v45 offset:0
	ds_read_b32 v62, v45 offset:64
	ds_read_b32 v47, v44 offset:16400
	ds_read_b32 v55, v45 offset:1024
	ds_read_b32 v63, v45 offset:1088
	ds_read_b32 v48, v44 offset:16416
	ds_read_b32 v56, v45 offset:2048
	ds_read_b32 v64, v45 offset:2112
	ds_read_b32 v49, v44 offset:16432
	ds_read_b32 v57, v45 offset:3072
	ds_read_b32 v65, v45 offset:3136
	ds_read_b32 v50, v44 offset:16448
	ds_read_b32 v58, v45 offset:4096
	ds_read_b32 v66, v45 offset:4160
	ds_read_b32 v51, v44 offset:16464
	ds_read_b32 v59, v45 offset:5120
	ds_read_b32 v67, v45 offset:5184
	ds_read_b32 v52, v44 offset:16480
	ds_read_b32 v60, v45 offset:6144
	ds_read_b32 v68, v45 offset:6208
	ds_read_b32 v53, v44 offset:16496
	ds_read_b32 v61, v45 offset:7168
	ds_read_b32 v69, v45 offset:7232
	s_waitcnt lgkmcnt(0)
	v_mfma_f32_16x16x4_f32 v[70:73], v46, v54, 0
	v_mfma_f32_16x16x4_f32 v[74:77], v46, v62, 0
	v_mfma_f32_16x16x4_f32 v[70:73], v47, v55, v[70:73]
	v_mfma_f32_16x16x4_f32 v[74:77], v47, v63, v[74:77]
	v_mfma_f32_16x16x4_f32 v[70:73], v48, v56, v[70:73]
	v_mfma_f32_16x16x4_f32 v[74:77], v48, v64, v[74:77]
	v_mfma_f32_16x16x4_f32 v[70:73], v49, v57, v[70:73]
	v_mfma_f32_16x16x4_f32 v[74:77], v49, v65, v[74:77]
	v_mfma_f32_16x16x4_f32 v[70:73], v50, v58, v[70:73]
	v_mfma_f32_16x16x4_f32 v[74:77], v50, v66, v[74:77]
	v_mfma_f32_16x16x4_f32 v[70:73], v51, v59, v[70:73]
	v_mfma_f32_16x16x4_f32 v[74:77], v51, v67, v[74:77]
	v_mfma_f32_16x16x4_f32 v[70:73], v52, v60, v[70:73]
	v_mfma_f32_16x16x4_f32 v[74:77], v52, v68, v[74:77]
	v_mfma_f32_16x16x4_f32 v[70:73], v53, v61, v[70:73]
	v_mfma_f32_16x16x4_f32 v[74:77], v53, v69, v[74:77]
	ds_read_b32 v46, v44 offset:16512
	ds_read_b32 v54, v45 offset:8192
	ds_read_b32 v62, v45 offset:8256
	ds_read_b32 v47, v44 offset:16528
	ds_read_b32 v55, v45 offset:9216
	ds_read_b32 v63, v45 offset:9280
	ds_read_b32 v48, v44 offset:16544
	ds_read_b32 v56, v45 offset:10240
	ds_read_b32 v64, v45 offset:10304
	ds_read_b32 v49, v44 offset:16560
	ds_read_b32 v57, v45 offset:11264
	ds_read_b32 v65, v45 offset:11328
	ds_read_b32 v50, v44 offset:16576
	ds_read_b32 v58, v45 offset:12288
	ds_read_b32 v66, v45 offset:12352
	ds_read_b32 v51, v44 offset:16592
	ds_read_b32 v59, v45 offset:13312
	ds_read_b32 v67, v45 offset:13376
	ds_read_b32 v52, v44 offset:16608
	ds_read_b32 v60, v45 offset:14336
	ds_read_b32 v68, v45 offset:14400
	ds_read_b32 v53, v44 offset:16624
	ds_read_b32 v61, v45 offset:15360
	ds_read_b32 v69, v45 offset:15424
	s_waitcnt lgkmcnt(0)
	v_mfma_f32_16x16x4_f32 v[70:73], v46, v54, v[70:73]
	v_mfma_f32_16x16x4_f32 v[74:77], v46, v62, v[74:77]
	v_mfma_f32_16x16x4_f32 v[70:73], v47, v55, v[70:73]
	v_mfma_f32_16x16x4_f32 v[74:77], v47, v63, v[74:77]
	v_mfma_f32_16x16x4_f32 v[70:73], v48, v56, v[70:73]
	v_mfma_f32_16x16x4_f32 v[74:77], v48, v64, v[74:77]
	v_mfma_f32_16x16x4_f32 v[70:73], v49, v57, v[70:73]
	v_mfma_f32_16x16x4_f32 v[74:77], v49, v65, v[74:77]
	v_mfma_f32_16x16x4_f32 v[70:73], v50, v58, v[70:73]
	v_mfma_f32_16x16x4_f32 v[74:77], v50, v66, v[74:77]
	v_mfma_f32_16x16x4_f32 v[70:73], v51, v59, v[70:73]
	v_mfma_f32_16x16x4_f32 v[74:77], v51, v67, v[74:77]
	v_mfma_f32_16x16x4_f32 v[70:73], v52, v60, v[70:73]
	v_mfma_f32_16x16x4_f32 v[74:77], v52, v68, v[74:77]
	v_mfma_f32_16x16x4_f32 v[70:73], v53, v61, v[70:73]
	v_mfma_f32_16x16x4_f32 v[74:77], v53, v69, v[74:77]
	v_mul_u32_u24_e32 v50, 0x90, v42
	s_mulk_i32 s13, 0x90
	s_lshl_b32 s12, s12, 5
	v_lshl_add_u32 v50, v43, 3, v50
	s_add_i32 s12, s12, s13
	v_add_u32_e32 v50, s12, v50
	s_nop 7
	s_nop 3
	v_cvt_pk_bf16_f32 v46, v70, v71
	v_cvt_pk_bf16_f32 v47, v72, v73
	v_cvt_pk_bf16_f32 v48, v74, v75
	v_cvt_pk_bf16_f32 v49, v76, v77
	ds_write_b64 v50, v[46:47] offset:36864
	ds_write_b64 v50, v[48:49] offset:39168
	s_and_b64 s[4:5], s[4:5], exec
	s_cselect_b32 s12, s20, 0xa00
	s_and_b64 s[4:5], s[10:11], exec
	s_cselect_b32 s4, 0x400, s12
	s_mov_b32 s5, s9
	s_mul_hi_i32 s10, s26, 0xc00
	s_mulk_i32 s26, 0xc00
	s_or_b64 s[4:5], s[4:5], s[8:9]
	s_add_u32 s4, s4, s26
	s_addc_u32 s5, s5, s10
	s_waitcnt lgkmcnt(0)
	s_barrier
	ds_read_b128 v[42:45], v16 offset:36864
	v_lshl_add_u64 v[12:13], s[4:5], 0, v[8:9]
	v_lshlrev_b64 v[12:13], 11, v[12:13]
	v_lshl_add_u64 v[12:13], s[6:7], 0, v[12:13]
	s_lshl_b32 s8, s27, 1
	v_lshl_add_u64 v[12:13], v[12:13], 0, s[8:9]
	s_add_i32 s21, s21, s54
	v_lshl_add_u64 v[12:13], v[12:13], 0, v[6:7]
	s_cmpk_gt_i32 s21, 0x2ff
	s_waitcnt lgkmcnt(0)
	global_store_dwordx4 v[12:13], v[42:45], off
	s_barrier
	s_cbranch_scc0 .LBB0_55
